# prologue weight-conversion tile: 8 gain loads issued together after the data loads with counted vmcnt waits (was one load + vmcnt(0) round trip per LDS write step)
# speedup vs baseline: 1.0096x; 1.0096x over previous
; #define GPTR(T, ptr) ((__attribute__((address_space(1))) T*)(ptr))
; __device__ void cvt_tile(const CvtJob& c, int tile, bfu* wt, const int tid_) {
;     ...
;   const int tid = tid_;
;   __syncthreads();
;   { f32x4 v[8];
;     _Pragma("unroll") for (int i = 0; i < 8; ++i) { const int idx = tid + 512 * i; const int kk = idx >> 4, n4 = idx & 15;
;       v[i] = *GPTR(const f32x4, src + (long)(k0 + kk) * c.ld + l0 + n4 * 4); }
;     _Pragma("unroll") for (int i = 0; i < 8; ++i) { const int idx = tid + 512 * i; const int kk = idx >> 4, n4 = idx & 15;
;       const float gsc = c.gain ? c.gain[k0 + kk] : 1.0f;
;       _Pragma("unroll") for (int e = 0; e < 4; ++e) ts[kk * 65 + n4 * 4 + e] = v[i][e] * gsc; } }
.LBB0_680:
	s_ashr_i32 s0, s2, 31
	s_lshr_b32 s0, s0, 30
	s_add_i32 s0, s2, s0
	s_ashr_i32 s14, s0, 2
	s_lshl_b32 s13, s14, 6
	s_or_b32 s0, s13, 8
	s_cmpk_lt_i32 s2, 0x80
	s_cselect_b32 s0, s13, s0
	s_ashr_i32 s1, s0, 31
	v_readlane_b32 s36, v253, 52
	v_mbcnt_lo_u32_b32 v56, -1, 0
	v_mbcnt_hi_u32_b32 v56, -1, v56
	s_lshl_b64 s[0:1], s[0:1], 2
	v_readlane_b32 s44, v253, 60
	v_lshlrev_b32_e32 v0, 2, v56
	v_or_b32_e32 v55, s33, v56
	v_readlane_b32 s45, v253, 61
	s_add_u32 s0, s44, s0
	v_and_b32_e32 v47, 60, v0
	s_addc_u32 s1, s45, s1
	v_lshlrev_b32_e32 v0, 2, v47
	v_ashrrev_i32_e32 v58, 4, v55
	s_lshl_b32 s14, s14, 10
	v_add_u32_e32 v54, 0x200, v55
	s_waitcnt lgkmcnt(0)
	v_lshl_add_u64 v[2:3], s[0:1], 0, v[0:1]
	v_subrev_u32_e32 v0, s14, v58
	v_ashrrev_i32_e32 v45, 4, v54
	v_add_u32_e32 v53, 0x400, v55
	v_add_u32_e32 v48, s3, v0
	v_subrev_u32_e32 v0, s14, v45
	v_ashrrev_i32_e32 v43, 4, v53
	v_add_u32_e32 v51, 0x600, v55
	v_add_u32_e32 v46, s3, v0
	v_subrev_u32_e32 v0, s14, v43
	v_ashrrev_i32_e32 v41, 4, v51
	v_add_u32_e32 v44, s3, v0
	v_subrev_u32_e32 v0, s14, v41
	v_add_u32_e32 v42, s3, v0
	v_add_u32_e32 v0, 0x800, v55
	v_ashrrev_i32_e32 v39, 4, v0
	v_subrev_u32_e32 v0, s14, v39
	v_add_u32_e32 v40, s3, v0
	v_add_u32_e32 v0, 0xa00, v55
	v_ashrrev_i32_e32 v37, 4, v0
	v_subrev_u32_e32 v0, s14, v37
	v_add_u32_e32 v38, s3, v0
	v_add_u32_e32 v0, 0xc00, v55
	v_ashrrev_i32_e32 v35, 4, v0
	v_subrev_u32_e32 v0, s14, v35
	v_add_u32_e32 v36, s3, v0
	v_add_u32_e32 v0, 0xe00, v55
	v_mad_i64_i32 v[4:5], s[0:1], v48, s20, v[2:3]
	v_ashrrev_i32_e32 v57, 4, v0
	s_waitcnt vmcnt(0)
	s_barrier
	v_mad_i64_i32 v[6:7], s[0:1], v46, s20, v[2:3]
	global_load_dwordx4 v[30:33], v[4:5], off
	global_load_dwordx4 v[26:29], v[6:7], off
	v_mad_i64_i32 v[4:5], s[0:1], v44, s20, v[2:3]
	v_subrev_u32_e32 v0, s14, v57
	v_mad_i64_i32 v[6:7], s[0:1], v42, s20, v[2:3]
	global_load_dwordx4 v[22:25], v[4:5], off
	global_load_dwordx4 v[18:21], v[6:7], off
	v_mad_i64_i32 v[4:5], s[0:1], v40, s20, v[2:3]
	v_add_u32_e32 v34, s3, v0
	v_mad_i64_i32 v[6:7], s[0:1], v38, s20, v[2:3]
	global_load_dwordx4 v[14:17], v[4:5], off
	global_load_dwordx4 v[10:13], v[6:7], off
	v_mad_i64_i32 v[4:5], s[0:1], v36, s20, v[2:3]
	v_mad_i64_i32 v[2:3], s[0:1], v34, s20, v[2:3]
	global_load_dwordx4 v[6:9], v[4:5], off
	s_nop 0
	global_load_dwordx4 v[2:5], v[2:3], off
	v_readlane_b32 s18, v252, 28
	v_readlane_b32 s19, v252, 29
	v_readlane_b32 s38, v253, 54
	v_readlane_b32 s39, v253, 55
	v_readlane_b32 s37, v253, 53
	v_readlane_b32 s40, v253, 56
	v_readlane_b32 s41, v253, 57
	v_readlane_b32 s42, v253, 58
	v_readlane_b32 s43, v253, 59
	v_readlane_b32 s46, v253, 62
	v_readlane_b32 s47, v253, 63
	v_readlane_b32 s48, v254, 0
	v_readlane_b32 s49, v254, 1
	v_readlane_b32 s50, v254, 2
	v_readlane_b32 s51, v254, 3
	v_mov_b32_e32 v46, 1.0
	v_mov_b32_e32 v44, 1.0
	v_mov_b32_e32 v42, 1.0
	v_mov_b32_e32 v40, 1.0
	v_mov_b32_e32 v38, 1.0
	v_mov_b32_e32 v36, 1.0
	v_mov_b32_e32 v34, 1.0
	v_mov_b32_e32 v50, 1.0
	s_andn2_b64 vcc, exec, s[18:19]
	s_cbranch_vccnz .Lcvt0_nogain
	v_lshlrev_b32_e32 v52, 2, v48
	global_load_dword v46, v52, s[38:39]
	global_load_dword v44, v52, s[38:39] offset:128
	global_load_dword v42, v52, s[38:39] offset:256
	global_load_dword v40, v52, s[38:39] offset:384
	global_load_dword v38, v52, s[38:39] offset:512
	global_load_dword v36, v52, s[38:39] offset:640
	global_load_dword v34, v52, s[38:39] offset:768
	global_load_dword v50, v52, s[38:39] offset:896
.Lcvt0_nogain:
	v_lshl_add_u32 v0, v47, 2, 0
	v_mad_u32_u24 v48, v58, s75, v0
	s_waitcnt vmcnt(7)
	v_pk_mul_f32 v[30:31], v[30:31], v[46:47] op_sel_hi:[1,0]
	v_pk_mul_f32 v[32:33], v[32:33], v[46:47] op_sel_hi:[1,0]
	ds_write2_b32 v48, v30, v31 offset1:1
	ds_write2_b32 v48, v32, v33 offset0:2 offset1:3
	v_mad_u32_u24 v48, v45, s75, v0
	s_waitcnt vmcnt(6)
	v_pk_mul_f32 v[26:27], v[26:27], v[44:45] op_sel_hi:[1,0]
	v_pk_mul_f32 v[28:29], v[28:29], v[44:45] op_sel_hi:[1,0]
	ds_write2_b32 v48, v26, v27 offset1:1
	ds_write2_b32 v48, v28, v29 offset0:2 offset1:3
	v_mad_u32_u24 v48, v43, s75, v0
	s_waitcnt vmcnt(5)
	v_pk_mul_f32 v[22:23], v[22:23], v[42:43] op_sel_hi:[1,0]
	v_pk_mul_f32 v[24:25], v[24:25], v[42:43] op_sel_hi:[1,0]
	ds_write2_b32 v48, v22, v23 offset1:1
	ds_write2_b32 v48, v24, v25 offset0:2 offset1:3
	v_mad_u32_u24 v48, v41, s75, v0
	s_waitcnt vmcnt(4)
	v_pk_mul_f32 v[18:19], v[18:19], v[40:41] op_sel_hi:[1,0]
	v_pk_mul_f32 v[20:21], v[20:21], v[40:41] op_sel_hi:[1,0]
	ds_write2_b32 v48, v18, v19 offset1:1
	ds_write2_b32 v48, v20, v21 offset0:2 offset1:3
	v_mad_u32_u24 v48, v39, s75, v0
	s_waitcnt vmcnt(3)
	v_pk_mul_f32 v[14:15], v[14:15], v[38:39] op_sel_hi:[1,0]
	v_pk_mul_f32 v[16:17], v[16:17], v[38:39] op_sel_hi:[1,0]
	ds_write2_b32 v48, v14, v15 offset1:1
	ds_write2_b32 v48, v16, v17 offset0:2 offset1:3
	v_mad_u32_u24 v48, v37, s75, v0
	s_waitcnt vmcnt(2)
	v_pk_mul_f32 v[10:11], v[10:11], v[36:37] op_sel_hi:[1,0]
	v_pk_mul_f32 v[12:13], v[12:13], v[36:37] op_sel_hi:[1,0]
	ds_write2_b32 v48, v10, v11 offset1:1
	ds_write2_b32 v48, v12, v13 offset0:2 offset1:3
	v_mad_u32_u24 v48, v35, s75, v0
	s_waitcnt vmcnt(1)
	v_pk_mul_f32 v[6:7], v[6:7], v[34:35] op_sel_hi:[1,0]
	v_pk_mul_f32 v[8:9], v[8:9], v[34:35] op_sel_hi:[1,0]
	ds_write2_b32 v48, v6, v7 offset1:1
	ds_write2_b32 v48, v8, v9 offset0:2 offset1:3
	s_waitcnt vmcnt(0)
	v_mov_b32_e32 v10, v50
	s_branch .LBB0_679
